# P7c coefficient exchange via DPP cndmask at loop top, wave sum via row_bcast, dead lane-offset code removed
# baseline (speedup 1.0000x reference)
; __device__ __forceinline__ int fresh_lane() { int l; asm volatile("v_mbcnt_lo_u32_b32 %0, -1, 0\n\tv_mbcnt_hi_u32_b32 %0, -1, %0" : "=v"(l)); return l; }
; __device__ __forceinline__ unsigned xb_ld(unsigned* p)              { return __hip_atomic_load(p, __ATOMIC_RELAXED, __HIP_MEMORY_SCOPE_AGENT); }
; __device__ __forceinline__ SliceOwn slice_census(unsigned* bar, unsigned x) {
;     SliceOwn s; s.n_mine = 1u; s.vx = 0u; s.npop = 0u;
; #pragma unroll
;     for (unsigned j = 0; j < 16; ++j) { const unsigned c = (unsigned)__builtin_amdgcn_readfirstlane((int)xb_ld(&bar[XB_XCNT(j)])); if (c > 0u) { if (j < x) ++s.vx; ++s.npop; } if (j == x) s.n_mine = c > 0u ? c : 1u; }
;     if (s.npop == 0u) s.npop = 1u;
;     return s;
; }
; __device__ __forceinline__ void p7c_vaxpy(Frame& F, unsigned* bar, unsigned x, unsigned rank) {
;     const int lane = fresh_lane(), r = lane >> 3, seg = lane & 7;
;     const SliceOwn so = slice_census(bar, x);
;     const int gwl = (int)rank * NWAVES + F.wave, stride = (int)so.n_mine * NWAVES;
;     const unsigned char* RE16b = F.ws + WS_RE16; const unsigned char* CQb = F.ws + WS_CQ; const float* SCQ = (const float*)(F.ws + WS_SCQ);
;     float* SS3 = (float*)(F.ws + WS_SS3); bf16* X2Bw = (bf16*)(F.ws + WS_X2B);
.LBB0_1082:
	s_or_b64 exec, exec, s[0:1]
	s_waitcnt vmcnt(31)
	v_mov_b32_e32 v157, 0
	s_waitcnt lgkmcnt(0)
	s_barrier
	v_mbcnt_lo_u32_b32 v6, -1, 0
	v_mbcnt_hi_u32_b32 v6, -1, v6
	global_load_dword v0, v157, s[66:67] offset:1024 sc1
	global_load_dword v2, v157, s[66:67] offset:1280 sc1
	v_readlane_b32 s4, v254, 36
	v_readlane_b32 s5, v254, 37
	v_readlane_b32 s6, v254, 40
	v_readlane_b32 s7, v254, 41
	v_readlane_b32 s8, v255, 5
	v_readlane_b32 s9, v255, 6
	v_readlane_b32 s10, v254, 46
	v_readlane_b32 s11, v254, 47
	v_ashrrev_i32_e32 v12, 3, v6
	v_readlane_b32 s12, v255, 9
	v_readlane_b32 s13, v255, 10
	s_mov_b32 s22, 0
	s_mov_b32 s25, 0x5040100
	s_mov_b32 s26, 0x7060302
	v_mov_b32_e32 v194, 7
	s_waitcnt vmcnt(1)
	v_readfirstlane_b32 s2, v0
	s_waitcnt vmcnt(0)
	v_readfirstlane_b32 s3, v2
	global_load_dword v2, v157, s[66:67] offset:1536 sc1
	global_load_dword v3, v157, s[66:67] offset:1792 sc1
	global_load_dword v4, v157, s[66:67] offset:2048 sc1
	global_load_dword v5, v157, s[66:67] offset:2304 sc1
	global_load_dword v7, v157, s[66:67] offset:2560 sc1
	global_load_dword v8, v157, s[66:67] offset:2816 sc1
	global_load_dword v9, v157, s[66:67] offset:3072 sc1
	global_load_dword v10, v157, s[66:67] offset:3328 sc1
	global_load_dword v13, v157, s[66:67] offset:3584 sc1
	global_load_dword v14, v157, s[66:67] offset:3840 sc1
	global_load_dword v15, v157, s[46:47] sc1
	global_load_dword v16, v157, s[48:49] sc1
	global_load_dword v17, v157, s[50:51] sc1
	global_load_dword v18, v157, s[52:53] sc1
	s_cmp_lg_u32 s2, 0
	s_cselect_b64 s[0:1], -1, 0
	v_cndmask_b32_e64 v0, 0, 1, s[0:1]
	s_and_b64 s[0:1], s[4:5], s[0:1]
	s_max_u32 s2, s2, 1
	v_cndmask_b32_e64 v1, 0, 1, s[0:1]
	s_and_b64 s[0:1], s[70:71], exec
	s_cselect_b32 s2, s2, 1
	s_cmp_lg_u32 s3, 0
	s_cselect_b64 vcc, -1, 0
	v_addc_co_u32_e64 v0, s[0:1], 0, v0, vcc
	v_readlane_b32 s0, v254, 38
	v_readlane_b32 s1, v254, 39
	s_and_b64 s[0:1], s[0:1], vcc
	s_max_u32 s3, s3, 1
	v_cndmask_b32_e64 v11, 0, 1, s[0:1]
	s_and_b64 s[0:1], s[72:73], exec
	s_cselect_b32 s2, s3, s2
	v_add_u32_e32 v1, v11, v1
	s_waitcnt vmcnt(13)
	v_readfirstlane_b32 s4, v2
	s_cmp_lg_u32 s4, 0
	s_cselect_b64 s[0:1], -1, 0
	v_cndmask_b32_e64 v2, 0, 1, s[0:1]
	s_and_b64 s[0:1], s[6:7], s[0:1]
	s_max_u32 s4, s4, 1
	s_waitcnt vmcnt(12)
	v_readfirstlane_b32 s3, v3
	v_cndmask_b32_e64 v3, 0, 1, s[0:1]
	s_and_b64 s[0:1], s[74:75], exec
	s_cselect_b32 s2, s4, s2
	s_cmp_lg_u32 s3, 0
	s_cselect_b64 vcc, -1, 0
	v_addc_co_u32_e64 v0, s[0:1], v0, v2, vcc
	v_readlane_b32 s0, v255, 3
	v_readlane_b32 s1, v255, 4
	s_and_b64 s[0:1], s[0:1], vcc
	s_max_u32 s3, s3, 1
	s_waitcnt vmcnt(11)
	v_readfirstlane_b32 s5, v4
	v_cndmask_b32_e64 v2, 0, 1, s[0:1]
	s_and_b64 s[0:1], s[76:77], exec
	s_cselect_b32 s2, s3, s2
	s_cmp_lg_u32 s5, 0
	s_cselect_b64 s[0:1], -1, 0
	v_cndmask_b32_e64 v4, 0, 1, s[0:1]
	s_and_b64 s[0:1], s[8:9], s[0:1]
	v_add_u32_e32 v1, v1, v3
	s_max_u32 s5, s5, 1
	s_waitcnt vmcnt(10)
	v_readfirstlane_b32 s4, v5
	v_add_u32_e32 v1, v1, v2
	v_cndmask_b32_e64 v2, 0, 1, s[0:1]
	s_and_b64 s[0:1], s[78:79], exec
	s_cselect_b32 s2, s5, s2
	s_cmp_lg_u32 s4, 0
	s_cselect_b64 vcc, -1, 0
	v_addc_co_u32_e64 v0, s[0:1], v0, v4, vcc
	v_readlane_b32 s0, v255, 1
	v_readlane_b32 s1, v255, 2
	s_max_u32 s4, s4, 1
	s_and_b64 s[0:1], s[0:1], vcc
	s_waitcnt vmcnt(9)
	v_readfirstlane_b32 s6, v7
	v_add_u32_e32 v1, v1, v2
	v_cndmask_b32_e64 v2, 0, 1, s[0:1]
	s_and_b64 s[0:1], s[80:81], exec
	s_cselect_b32 s2, s4, s2
	s_cmp_lg_u32 s6, 0
	s_cselect_b64 s[0:1], -1, 0
	v_add_u32_e32 v1, v1, v2
	v_cndmask_b32_e64 v2, 0, 1, s[0:1]
	s_max_u32 s4, s6, 1
	s_and_b64 s[0:1], s[10:11], s[0:1]
	s_waitcnt vmcnt(8)
	v_readfirstlane_b32 s7, v8
	v_cndmask_b32_e64 v3, 0, 1, s[0:1]
	s_and_b64 s[0:1], s[84:85], exec
	s_cselect_b32 s2, s4, s2
	s_cmp_lg_u32 s7, 0
	s_cselect_b64 vcc, -1, 0
	v_addc_co_u32_e64 v0, s[0:1], v0, v2, vcc
	v_readlane_b32 s0, v254, 44
	v_readlane_b32 s1, v254, 45
	s_max_u32 s4, s7, 1
	s_and_b64 s[0:1], s[0:1], vcc
	s_waitcnt vmcnt(7)
	v_readfirstlane_b32 s3, v9
	v_cndmask_b32_e64 v2, 0, 1, s[0:1]
	s_and_b64 s[0:1], s[86:87], exec
	s_cselect_b32 s2, s4, s2
	s_cmp_lg_u32 s3, 0
	v_readlane_b32 s4, v254, 42
	v_add_u32_e32 v1, v1, v3
	s_cselect_b64 s[0:1], -1, 0
	v_readlane_b32 s5, v254, 43
	v_add_u32_e32 v1, v1, v2
	v_cndmask_b32_e64 v2, 0, 1, s[0:1]
	s_max_u32 s3, s3, 1
	s_and_b64 s[0:1], s[4:5], s[0:1]
	s_waitcnt vmcnt(6)
	v_readfirstlane_b32 s8, v10
	v_cndmask_b32_e64 v3, 0, 1, s[0:1]
	s_and_b64 s[0:1], s[88:89], exec
	s_cselect_b32 s2, s3, s2
	s_cmp_lg_u32 s8, 0
	s_cselect_b64 vcc, -1, 0
	v_addc_co_u32_e64 v0, s[0:1], v0, v2, vcc
	v_readlane_b32 s0, v254, 34
	v_readlane_b32 s1, v254, 35
	s_and_b64 s[0:1], s[0:1], vcc
	s_max_u32 s3, s8, 1
	v_cndmask_b32_e64 v2, 0, 1, s[0:1]
	s_and_b64 s[0:1], s[90:91], exec
	s_cselect_b32 s2, s3, s2
	s_waitcnt vmcnt(5)
	v_readfirstlane_b32 s3, v13
	s_cmp_lg_u32 s3, 0
	v_readlane_b32 s4, v255, 41
	v_add_u32_e32 v1, v1, v3
	s_cselect_b64 s[0:1], -1, 0
	v_readlane_b32 s5, v255, 42
	v_add_u32_e32 v1, v1, v2
	v_cndmask_b32_e64 v2, 0, 1, s[0:1]
	s_and_b64 s[0:1], s[4:5], s[0:1]
	s_max_u32 s3, s3, 1
	v_cndmask_b32_e64 v3, 0, 1, s[0:1]
	s_and_b64 s[0:1], s[92:93], exec
	s_cselect_b32 s2, s3, s2
	s_waitcnt vmcnt(4)
	v_readfirstlane_b32 s3, v14
	s_cmp_lg_u32 s3, 0
	s_cselect_b64 vcc, -1, 0
	v_addc_co_u32_e64 v0, s[0:1], v0, v2, vcc
	v_readlane_b32 s0, v255, 43
	v_readlane_b32 s1, v255, 44
	s_and_b64 s[0:1], s[0:1], vcc
	s_max_u32 s3, s3, 1
	v_cndmask_b32_e64 v2, 0, 1, s[0:1]
	s_and_b64 s[0:1], s[94:95], exec
	s_cselect_b32 s2, s3, s2
	s_waitcnt vmcnt(3)
; __device__ __forceinline__ int fresh_lane() { int l; asm volatile("v_mbcnt_lo_u32_b32 %0, -1, 0\n\tv_mbcnt_hi_u32_b32 %0, -1, %0" : "=v"(l)); return l; }
; __device__ __forceinline__ void p7c_vaxpy(Frame& F, unsigned* bar, unsigned x, unsigned rank) {
;     const int lane = fresh_lane(), r = lane >> 3, seg = lane & 7;
;     const SliceOwn so = slice_census(bar, x);
;     const int gwl = (int)rank * NWAVES + F.wave, stride = (int)so.n_mine * NWAVES;
;     const unsigned char* RE16b = F.ws + WS_RE16; const unsigned char* CQb = F.ws + WS_CQ; const float* SCQ = (const float*)(F.ws + WS_SCQ);
;     float* SS3 = (float*)(F.ws + WS_SS3); bf16* X2Bw = (bf16*)(F.ws + WS_X2B);
; #pragma unroll 1
;     for (int pass = 0; pass < 16; ++pass) {
;         const int hs = (2 * (int)so.vx + pass) & 15; if ((unsigned)(hs >> 1) % so.npop != so.vx) continue;
;         const unsigned char* Vb = F.ws + WS_V + (size_t)hs * (16384 * 128) + 16 * seg;
;         const unsigned char* rp0 = RE16b + r * 32; const unsigned char* cp0 = CQb + r * 16;
	v_readfirstlane_b32 s3, v15
	s_cmp_lg_u32 s3, 0
	v_readlane_b32 s4, v255, 45
	v_add_u32_e32 v1, v1, v3
	s_cselect_b64 s[0:1], -1, 0
	v_readlane_b32 s5, v255, 46
	v_add_u32_e32 v1, v1, v2
	v_cndmask_b32_e64 v2, 0, 1, s[0:1]
	s_and_b64 s[0:1], s[4:5], s[0:1]
	v_cndmask_b32_e64 v3, 0, 1, s[0:1]
	v_readlane_b32 s0, v254, 7
	s_max_u32 s3, s3, 1
	v_readlane_b32 s1, v254, 8
	s_and_b64 s[0:1], s[0:1], exec
	s_cselect_b32 s2, s3, s2
	s_waitcnt vmcnt(2)
	v_readfirstlane_b32 s3, v16
	s_cmp_lg_u32 s3, 0
	s_cselect_b64 vcc, -1, 0
	v_addc_co_u32_e64 v0, s[0:1], v0, v2, vcc
	v_readlane_b32 s0, v255, 47
	v_readlane_b32 s1, v255, 48
	s_and_b64 s[0:1], s[0:1], vcc
	s_max_u32 s3, s3, 1
	v_cndmask_b32_e64 v2, 0, 1, s[0:1]
	v_readlane_b32 s0, v255, 39
	v_readlane_b32 s1, v255, 40
	s_and_b64 s[0:1], s[0:1], exec
	s_cselect_b32 s2, s3, s2
	s_waitcnt vmcnt(1)
	v_readfirstlane_b32 s3, v17
	s_cmp_lg_u32 s3, 0
	v_readlane_b32 s4, v254, 51
	v_add_u32_e32 v1, v1, v3
	s_cselect_b64 s[0:1], -1, 0
	v_readlane_b32 s5, v254, 52
	v_add_u32_e32 v1, v1, v2
	v_cndmask_b32_e64 v2, 0, 1, s[0:1]
	s_and_b64 s[0:1], s[4:5], s[0:1]
	v_cndmask_b32_e64 v3, 0, 1, s[0:1]
	v_readlane_b32 s0, v255, 37
	s_max_u32 s3, s3, 1
	v_readlane_b32 s1, v255, 38
	s_and_b64 s[0:1], s[0:1], exec
	s_waitcnt vmcnt(0)
	v_readfirstlane_b32 s0, v18
	s_cselect_b32 s2, s3, s2
	s_cmp_lg_u32 s0, 0
	s_cselect_b64 vcc, -1, 0
	v_addc_co_u32_e32 v0, vcc, v0, v2, vcc
	s_max_u32 s3, s0, 1
	s_and_b64 s[0:1], s[4:5], exec
	v_max_u32_e32 v191, 1, v0
	v_lshlrev_b32_e32 v0, 4, v6
	s_cselect_b32 s24, s3, s2
	s_lshl_b32 s0, s33, 3
	v_and_b32_e32 v156, 0x70, v0
	v_lshlrev_b32_e32 v0, 5, v12
	v_add_u32_e32 v190, v1, v3
	s_add_i32 s0, s0, s96
	s_lshl_b32 s23, s24, 3
	v_ashrrev_i32_e32 v1, 31, v0
	s_add_u32 s2, s66, 0x1de00000
	v_lshl_add_u64 v[158:159], s[42:43], 0, v[0:1]
	v_lshlrev_b32_e32 v0, 4, v12
	s_addc_u32 s3, s67, 0
	v_ashrrev_i32_e32 v1, 31, v0
	s_min_i32 s6, s0, 0x5fff
	v_lshl_add_u64 v[0:1], s[66:67], 0, v[0:1]
	s_mov_b64 s[4:5], 0x1da00000
	s_ashr_i32 s7, s6, 31
	v_lshl_add_u64 v[160:161], v[0:1], 0, s[4:5]
	s_lshl_b64 s[4:5], s[6:7], 8
	v_lshl_add_u64 v[162:163], v[158:159], 0, s[4:5]
	s_lshl_b64 s[4:5], s[6:7], 7
	v_lshl_add_u64 v[164:165], v[160:161], 0, s[4:5]
	s_lshl_b64 s[4:5], s[6:7], 2
	s_add_u32 s4, s54, s4
	s_addc_u32 s5, s55, s5
	s_lshl_b64 s[6:7], s[6:7], 12
	s_add_u32 s6, s40, s6
	s_addc_u32 s7, s41, s7
	s_add_i32 s1, s23, s0
	s_min_i32 s8, s1, 0x5fff
	v_and_b32_e32 v230, 0x30, v6
	v_and_b32_e32 v232, 15, v6
	v_lshlrev_b32_e32 v230, 2, v230
	v_lshl_add_u32 v230, v232, 1, v230
	v_and_b32_e32 v232, 1, v6
	v_mad_u32_u24 v0, v232, 30, v230
	v_mov_b32_e32 v1, v157
	s_ashr_i32 s9, s8, 31
	v_lshl_add_u64 v[2:3], s[6:7], 0, v[0:1]
	s_lshl_b64 s[6:7], s[8:9], 8
	v_lshl_add_u64 v[168:169], v[158:159], 0, s[6:7]
	s_lshl_b64 s[6:7], s[8:9], 7
	v_lshl_add_u64 v[170:171], v[160:161], 0, s[6:7]
	s_lshl_b64 s[6:7], s[8:9], 2
	s_add_u32 s6, s54, s6
	v_mov_b32_e32 v4, 0
	s_addc_u32 s7, s55, s7
	s_lshl_b64 s[8:9], s[8:9], 12
	v_ashrrev_i32_e32 v5, 31, v4
	s_add_u32 s8, s40, s8
	v_lshlrev_b64 v[4:5], 1, v[4:5]
	s_addc_u32 s9, s41, s9
	v_lshl_add_u64 v[166:167], v[2:3], 0, v[4:5]
	v_lshl_add_u64 v[2:3], s[8:9], 0, v[0:1]
	v_lshl_add_u64 v[0:1], s[40:41], 0, v[0:1]
	v_lshl_add_u64 v[174:175], v[0:1], 0, v[4:5]
	v_cvt_f32_u32_e32 v1, v191
	v_and_b32_e32 v0, 32, v6
	v_cmp_eq_u32_e64 s[36:37], 0, v0
	v_and_b32_e32 v0, 16, v6
	v_cmp_eq_u32_e64 s[38:39], 0, v0
	v_rcp_iflag_f32_e32 v0, v1
	s_cmpk_lt_i32 s0, 0x6000
	s_cselect_b64 s[8:9], -1, 0
	s_ashr_i32 s1, s0, 31
	v_mul_f32_e32 v0, 0x4f7ffffe, v0
	v_cvt_u32_f32_e32 v0, v0
	s_lshl_b32 s10, s24, 4
	v_and_b32_e32 v1, 8, v6
	v_lshl_add_u64 v[176:177], s[12:13], 0, v[156:157]
	s_lshl_b64 s[12:13], s[0:1], 6
	v_cmp_eq_u32_e64 s[40:41], 0, v1
	v_cmp_ne_u32_e64 s[60:61], 0, v1
	v_sub_u32_e32 v1, 0, v191
	s_add_u32 s11, s66, s12
	v_mul_lo_u32 v1, v1, v0
	s_addc_u32 s13, s67, s13
	v_mul_hi_u32 v1, v0, v1
	s_add_u32 s12, s11, 0x1de00000
	v_add_u32_e32 v193, v0, v1
	s_addc_u32 s13, s13, 0
	s_lshl_b64 s[16:17], s[0:1], 12
	v_and_b32_e32 v230, 0x30, v6
	v_and_b32_e32 v232, 15, v6
	v_lshlrev_b32_e32 v230, 2, v230
	v_lshl_add_u32 v230, v232, 1, v230
	v_and_b32_e32 v232, 1, v6
	v_mad_u32_u24 v0, v232, 30, v230
	v_or_b32_e32 v0, s16, v0
	v_mov_b32_e32 v1, s17
	v_lshl_add_u64 v[0:1], v[0:1], 0, v[4:5]
	v_lshlrev_b32_e32 v192, 1, v190
	s_ashr_i32 s11, s10, 31
	v_lshl_add_u64 v[0:1], s[66:67], 0, v[0:1]
	s_mov_b64 s[16:17], 0x16800000
	v_lshl_add_u64 v[172:173], v[2:3], 0, v[4:5]
	v_cmp_eq_u32_e64 s[42:43], 0, v6
	v_readlane_b32 s97, v254, 23
	v_and_b32_e32 v230, 1, v6
	v_cmp_eq_u32_e64 s[44:45], 0, v230
	s_nop 1
	s_lshl_b32 s97, s97, 14
	v_bfe_u32 v230, v6, 4, 1
	v_lshlrev_b32_e32 v230, 2, v230
	v_and_b32_e32 v232, 7, v6
	v_xor_b32_e32 v230, v230, v232
	v_and_b32_e32 v232, 0x38, v6
	v_lshlrev_b32_e32 v232, 4, v232
	v_lshl_add_u32 v230, v230, 4, v232
	v_add_u32_e32 v230, s97, v230
	v_xor_b32_e32 v208, 0, v230
	v_xor_b32_e32 v209, 16, v230
	v_xor_b32_e32 v210, 32, v230
	v_xor_b32_e32 v211, 48, v230
	v_bfe_u32 v230, v6, 1, 2
	v_lshrrev_b32_e32 v232, 4, v6
	v_lshlrev_b32_e32 v233, 10, v230
	v_lshl_add_u32 v233, v232, 8, v233
	v_and_b32_e32 v232, 1, v232
	v_lshl_or_b32 v230, v232, 2, v230
	v_bfe_u32 v232, v6, 3, 1
	v_lshl_add_u32 v233, v232, 7, v233
	v_and_b32_e32 v232, 1, v6
	v_lshl_add_u32 v233, v232, 3, v233
	v_add_u32_e32 v233, s97, v233
	v_xor_b32_e32 v232, 0, v230
	v_lshl_add_u32 v212, v232, 4, v233
	v_xor_b32_e32 v232, 1, v230
	v_lshl_add_u32 v213, v232, 4, v233
	v_xor_b32_e32 v232, 2, v230
	v_lshl_add_u32 v214, v232, 4, v233
	v_xor_b32_e32 v232, 3, v230
	v_lshl_add_u32 v215, v232, 4, v233
	v_xor_b32_e32 v232, 4, v230
	v_lshl_add_u32 v216, v232, 4, v233
	v_xor_b32_e32 v232, 5, v230
	v_lshl_add_u32 v217, v232, 4, v233
	v_xor_b32_e32 v232, 6, v230
	v_lshl_add_u32 v218, v232, 4, v233
	v_xor_b32_e32 v232, 7, v230
	v_lshl_add_u32 v219, v232, 4, v233
	s_mul_i32 s24, s24, 24
	s_lshl_b64 s[14:15], s[10:11], 6
	v_lshl_add_u64 v[178:179], v[0:1], 0, s[16:17]
	s_lshl_b64 s[16:17], s[10:11], 12
	s_mov_b32 s1, 0x5010400
	s_mov_b32 s11, 0x7030602
	v_mov_b32_e32 v195, v192
	s_branch .LBB0_1084

; #define P7C_LOADA(R0, R1, C, S, X, t) do { const int tt_ = (t) < NT_TOK ? (t) : NT_TOK - 1; const unsigned char* rp_ = rp0 + (size_t)tt_ * 256; R0 = *(const v4u*)rp_; R1 = *(const v4u*)(rp_ + 16); \
;             C = *(const v4u*)(cp0 + (size_t)tt_ * 128); S = SCQ[tt_]; X = *(const unsigned*)(X2Bw + (size_t)tt_ * DM + 128 * hs + 16 * seg + 2 * r); } while (0)
; #define P7C_ISSUE(G, R0, R1) do { __builtin_amdgcn_s_setprio(3); _Pragma("unroll") for (int i_ = 0; i_ < 16; ++i_) { const unsigned e_ = P7_EID(R0, R1, i_); G[i_] = *(const v4u*)(Vb + (size_t)e_ * 128); } __builtin_amdgcn_s_setprio(0); } while (0)
; __device__ __forceinline__ void p7c_vaxpy(Frame& F, unsigned* bar, unsigned x, unsigned rank) {
;     ...
;     for (int pass = 0; pass < 16; ++pass) {
;         const int hs = (2 * (int)so.vx + pass) & 15; if ((unsigned)(hs >> 1) % so.npop != so.vx) continue;
;         const unsigned char* Vb = F.ws + WS_V + (size_t)hs * (16384 * 128) + 16 * seg;
;         const unsigned char* rp0 = RE16b + r * 32; const unsigned char* cp0 = CQb + r * 16;
;     ...
;         v4u GA[16], GB[16], ra0, ra1, ca, rb0, rb1, cb, cA, cB; float sa, sb, sA, sB; unsigned xa, xb2, xA, xB;
;         P7C_LOADA(ra0, ra1, ca, sa, xa, gwl);
;         P7C_LOADA(rb0, rb1, cb, sb, xb2, gwl + stride);
;         P7C_ISSUE(GA, ra0, ra1); cA = ca; sA = sa; xA = xa;
.LBB0_1084:
	s_waitcnt vmcnt(23)
	v_add_u32_e32 v0, s22, v192
	v_bfe_u32 v1, v0, 1, 3
	v_mul_hi_u32 v2, v1, v193
	v_mul_lo_u32 v2, v2, v191
	v_sub_u32_e32 v1, v1, v2
	v_sub_u32_e32 v2, v1, v191
	v_cmp_ge_u32_e32 vcc, v1, v191
	s_nop 1
	v_cndmask_b32_e32 v1, v1, v2, vcc
	v_sub_u32_e32 v2, v1, v191
	v_cmp_ge_u32_e32 vcc, v1, v191
	s_nop 1
	v_cndmask_b32_e32 v1, v1, v2, vcc
	v_cmp_ne_u32_e32 vcc, v1, v190
	s_cbranch_vccnz .LBB0_1083
	v_and_b32_e32 v80, 15, v0
	v_lshlrev_b32_e32 v156, 21, v80
	v_lshl_add_u64 v[180:181], v[176:177], 0, v[156:157]
	s_nop 1
	v_readfirstlane_b32 s56, v180
	v_readfirstlane_b32 s57, v181
	s_movk_i32 s58, 0x80
	s_nop 3
	s_sub_u32 s56, s56, 0x80
	s_subb_u32 s57, s57, 0
	s_nop 3
	v_subrev_u32_e32 v200, s56, v180
	v_lshlrev_b32_e32 v156, 8, v80
	global_load_dwordx4 v[24:27], v[162:163], off offset:16
	global_load_dwordx4 v[8:11], v[162:163], off
	s_waitcnt vmcnt(4)
	v_lshl_add_u64 v[12:13], v[166:167], 0, v[156:157]
	global_load_dwordx4 v[0:3], v[164:165], off
	global_load_dwordx4 v[76:79], v[168:169], off
	global_load_dwordx4 v[64:67], v[168:169], off offset:16
	global_load_dwordx4 v[4:7], v[170:171], off
	v_lshl_add_u64 v[14:15], v[172:173], 0, v[156:157]
	global_load_dword v196, v157, s[4:5]
	global_load_dword v197, v[12:13], off
	global_load_dword v198, v157, s[6:7]
	global_load_dword v199, v[14:15], off
	s_setprio 3
	s_waitcnt vmcnt(8)
	v_mad_u32_u16 v12, v8, s58, v200 op_sel:[0,0,0,0]
	v_mad_u32_u16 v14, v8, s58, v200 op_sel:[1,0,0,0]
	global_load_dwordx4 v[48:51], v12, s[56:57]
	global_load_dwordx4 v[52:55], v14, s[56:57]
	v_mad_u32_u16 v12, v9, s58, v200 op_sel:[0,0,0,0]
	v_mad_u32_u16 v8, v9, s58, v200 op_sel:[1,0,0,0]
	global_load_dwordx4 v[68:71], v12, s[56:57]
	global_load_dwordx4 v[72:75], v8, s[56:57]
	v_mad_u32_u16 v8, v10, s58, v200 op_sel:[0,0,0,0]
	v_mad_u32_u16 v12, v10, s58, v200 op_sel:[1,0,0,0]
	global_load_dwordx4 v[32:35], v8, s[56:57]
	global_load_dwordx4 v[36:39], v12, s[56:57]
	v_mad_u32_u16 v8, v11, s58, v200 op_sel:[0,0,0,0]
	v_mad_u32_u16 v10, v11, s58, v200 op_sel:[1,0,0,0]
	global_load_dwordx4 v[56:59], v8, s[56:57]
	global_load_dwordx4 v[60:63], v10, s[56:57]
	v_mad_u32_u16 v8, v24, s58, v200 op_sel:[0,0,0,0]
	v_mad_u32_u16 v10, v24, s58, v200 op_sel:[1,0,0,0]
	global_load_dwordx4 v[16:19], v8, s[56:57]
	global_load_dwordx4 v[20:23], v10, s[56:57]
	v_mad_u32_u16 v8, v25, s58, v200 op_sel:[0,0,0,0]
	v_mad_u32_u16 v10, v25, s58, v200 op_sel:[1,0,0,0]
	global_load_dwordx4 v[40:43], v8, s[56:57]
	global_load_dwordx4 v[44:47], v10, s[56:57]
	v_mad_u32_u16 v8, v26, s58, v200 op_sel:[0,0,0,0]
	v_mad_u32_u16 v12, v26, s58, v200 op_sel:[1,0,0,0]
	v_mad_u32_u16 v24, v27, s58, v200 op_sel:[0,0,0,0]
	v_mad_u32_u16 v28, v27, s58, v200 op_sel:[1,0,0,0]
	global_load_dwordx4 v[8:11], v8, s[56:57]
	s_nop 0
	global_load_dwordx4 v[12:15], v12, s[56:57]
	s_nop 0
	global_load_dwordx4 v[24:27], v24, s[56:57]
	s_nop 0
	global_load_dwordx4 v[28:31], v28, s[56:57]
	s_setprio 0
	s_andn2_b64 vcc, exec, s[8:9]
	s_cbranch_vccnz .LBB0_1083
	v_lshlrev_b32_e32 v81, 7, v80
	v_lshlrev_b32_e32 v156, 1, v81
	v_lshl_add_u64 v[182:183], v[174:175], 0, v[156:157]
	v_lshlrev_b32_e32 v156, 2, v80
	v_and_b32_e32 v80, 15, v195
	v_lshl_add_u64 v[184:185], s[2:3], 0, v[156:157]
	v_lshlrev_b32_e32 v156, 2, v80
	v_lshl_add_u64 v[186:187], s[12:13], 0, v[156:157]
	v_lshlrev_b32_e32 v156, 8, v80
	v_lshl_add_u64 v[188:189], v[178:179], 0, v[156:157]
	s_mov_b32 s20, s0
	s_mov_b32 s98, 0x7fffffff
	s_mov_b32 s82, 0
	s_brev_b32 s83, 1
	s_branch .LBB0_1089

; #define P7C_LOADA(R0, R1, C, S, X, t) do { const int tt_ = (t) < NT_TOK ? (t) : NT_TOK - 1; const unsigned char* rp_ = rp0 + (size_t)tt_ * 256; R0 = *(const v4u*)rp_; R1 = *(const v4u*)(rp_ + 16); \
;             C = *(const v4u*)(cp0 + (size_t)tt_ * 128); S = SCQ[tt_]; X = *(const unsigned*)(X2Bw + (size_t)tt_ * DM + 128 * hs + 16 * seg + 2 * r); } while (0)
; #define P7C_ISSUE(G, R0, R1) do { __builtin_amdgcn_s_setprio(3); _Pragma("unroll") for (int i_ = 0; i_ < 16; ++i_) { const unsigned e_ = P7_EID(R0, R1, i_); G[i_] = *(const v4u*)(Vb + (size_t)e_ * 128); } __builtin_amdgcn_s_setprio(0); } while (0)
; __device__ __forceinline__ void p7c_vaxpy(Frame& F, unsigned* bar, unsigned x, unsigned rank) {
;     ...
;         v4u GA[16], GB[16], ra0, ra1, ca, rb0, rb1, cb, cA, cB; float sa, sb, sA, sB; unsigned xa, xb2, xA, xB;
;         P7C_LOADA(ra0, ra1, ca, sa, xa, gwl);
;         P7C_LOADA(rb0, rb1, cb, sb, xb2, gwl + stride);
;         P7C_ISSUE(GA, ra0, ra1); cA = ca; sA = sa; xA = xa;
; #pragma unroll 1
;         for (int t = gwl; t < NT_TOK; t += 2 * stride) {
;             P7C_LOADA(ra0, ra1, ca, sa, xa, t + 2 * stride); P7C_ISSUE(GB, rb0, rb1); cB = cb; sB = sb; xB = xb2; P7C_COMP(GA, cA, sA, xA, t);
;             P7C_LOADA(rb0, rb1, cb, sb, xb2, t + 3 * stride); P7C_ISSUE(GA, ra0, ra1); cA = ca; sA = sa; xA = xa; P7C_COMP(GB, cB, sB, xB, t + stride);
.LBB0_1089:
	s_add_i32 s27, s20, s10
	s_min_i32 s18, s27, 0x5fff
	s_ashr_i32 s19, s18, 31
	s_waitcnt vmcnt(23)
	s_mov_b64 vcc, s[40:41]
	v_cndmask_b32_dpp v220, v0, v0, vcc row_ror:8 row_mask:0xf bank_mask:0xf
	v_cndmask_b32_dpp v221, v1, v1, vcc row_ror:8 row_mask:0xf bank_mask:0xf
	v_cndmask_b32_dpp v222, v2, v2, vcc row_ror:8 row_mask:0xf bank_mask:0xf
	v_cndmask_b32_dpp v223, v3, v3, vcc row_ror:8 row_mask:0xf bank_mask:0xf
	s_lshl_b64 s[28:29], s[18:19], 8
	s_mov_b64 vcc, s[60:61]
	v_cndmask_b32_dpp v224, v0, v0, vcc row_ror:8 row_mask:0xf bank_mask:0xf
	v_cndmask_b32_dpp v225, v1, v1, vcc row_ror:8 row_mask:0xf bank_mask:0xf
	v_cndmask_b32_dpp v226, v2, v2, vcc row_ror:8 row_mask:0xf bank_mask:0xf
	v_cndmask_b32_dpp v227, v3, v3, vcc row_ror:8 row_mask:0xf bank_mask:0xf
	v_lshl_add_u64 v[0:1], v[158:159], 0, s[28:29]
	s_lshl_b64 s[28:29], s[18:19], 7
	global_load_dwordx4 v[144:147], v[0:1], off offset:16
	global_load_dwordx4 v[148:151], v[0:1], off
	v_lshl_add_u64 v[0:1], v[160:161], 0, s[28:29]
	s_lshl_b64 s[28:29], s[18:19], 2
	s_add_u32 s28, s54, s28
	s_addc_u32 s29, s55, s29
	s_lshl_b64 s[18:19], s[18:19], 12
	s_waitcnt vmcnt(20)
	v_mov_b32_e32 v206, v197
	v_mov_b32_e32 v207, v196
	v_lshl_add_u64 v[80:81], v[182:183], 0, s[18:19]
	global_load_dwordx4 v[0:3], v[0:1], off
	s_nop 0
	global_load_dword v196, v157, s[28:29]
	global_load_dword v197, v[80:81], off
	s_setprio 3
	v_permlane32_swap_b32_e32 v232, v236
	v_permlane32_swap_b32_e32 v233, v237
	v_mad_u32_u16 v80, v76, s58, v200 op_sel:[0,0,0,0]
	v_permlane32_swap_b32_e32 v234, v238
	v_permlane32_swap_b32_e32 v235, v239
	v_mad_u32_u16 v82, v76, s58, v200 op_sel:[1,0,0,0]
	v_add_u32_e32 v232, v232, v236
	v_add_u32_e32 v233, v233, v237
	global_load_dwordx4 v[128:131], v80, s[56:57]
	v_add_u32_e32 v234, v234, v238
	global_load_dwordx4 v[132:135], v82, s[56:57]
	v_add_u32_e32 v235, v235, v239
	v_mad_u32_u16 v80, v77, s58, v200 op_sel:[0,0,0,0]
	s_nop 1
	v_permlane16_swap_b32_e32 v232, v234
	v_mad_u32_u16 v76, v77, s58, v200 op_sel:[1,0,0,0]
	v_permlane16_swap_b32_e32 v233, v235
	global_load_dwordx4 v[136:139], v80, s[56:57]
	v_add_u32_e32 v232, v232, v234
	global_load_dwordx4 v[140:143], v76, s[56:57]
	v_add_u32_e32 v233, v233, v235
	s_nop 1
	v_mad_u32_u16 v76, v78, s58, v200 op_sel:[0,0,0,0]
	v_mov_b32_dpp v234, v232 quad_perm:[1,0,3,2] row_mask:0xf bank_mask:0xf
	v_mov_b32_dpp v235, v233 quad_perm:[1,0,3,2] row_mask:0xf bank_mask:0xf
	v_mad_u32_u16 v80, v78, s58, v200 op_sel:[1,0,0,0]
	v_cndmask_b32_e64 v236, v235, v232, s[44:45]
	global_load_dwordx4 v[112:115], v76, s[56:57]
	v_cndmask_b32_e64 v237, v233, v234, s[44:45]
	global_load_dwordx4 v[116:119], v80, s[56:57]
	v_cvt_f32_i32_e32 v236, v236
	v_cvt_f32_i32_e32 v237, v237
	v_mad_u32_u16 v76, v79, s58, v200 op_sel:[0,0,0,0]
	v_lshlrev_b32_e32 v238, 16, v204
	v_and_b32_e32 v239, 0xffff0000, v204
	v_mad_u32_u16 v78, v79, s58, v200 op_sel:[1,0,0,0]
	v_fmac_f32_e32 v238, v205, v236
	global_load_dwordx4 v[120:123], v76, s[56:57]
	v_fmac_f32_e32 v239, v205, v237
	global_load_dwordx4 v[124:127], v78, s[56:57]
	v_mul_f32_e32 v240, v239, v239
	v_fmac_f32_e32 v240, v238, v238
	v_mad_u32_u16 v76, v64, s58, v200 op_sel:[0,0,0,0]
	v_cvt_pk_bf16_f32 v244, v238, v239
	s_cmpk_gt_i32 s98, 0x5fff
	s_cbranch_scc1 .Lp7c_sk1_b
	s_ashr_i32 s99, s98, 31
	s_lshl_b64 s[100:101], s[98:99], 12
	v_lshl_add_u64 v[242:243], v[182:183], 0, s[100:101]
	global_store_dword v[242:243], v244, off
.Lp7c_sk1_b:
	v_mad_u32_u16 v78, v64, s58, v200 op_sel:[1,0,0,0]
	s_nop 1
	v_add_f32_dpp v240, v240, v240 quad_perm:[1,0,3,2] row_mask:0xf bank_mask:0xf
	global_load_dwordx4 v[96:99], v76, s[56:57]
	s_nop 1
	global_load_dwordx4 v[100:103], v78, s[56:57]
	v_add_f32_dpp v240, v240, v240 quad_perm:[2,3,0,1] row_mask:0xf bank_mask:0xf
	v_mad_u32_u16 v76, v65, s58, v200 op_sel:[0,0,0,0]
	s_nop 1
	v_add_f32_dpp v240, v240, v240 row_half_mirror row_mask:0xf bank_mask:0xf
	v_mad_u32_u16 v64, v65, s58, v200 op_sel:[1,0,0,0]
	s_nop 1
	global_load_dwordx4 v[104:107], v76, s[56:57]
	v_add_f32_dpp v240, v240, v240 row_mirror row_mask:0xf bank_mask:0xf
	global_load_dwordx4 v[108:111], v64, s[56:57]
	s_nop 1
	v_add_f32_dpp v240, v240, v240 row_bcast:15 row_mask:0xa bank_mask:0xf
	v_mad_u32_u16 v64, v66, s58, v200 op_sel:[0,0,0,0]
	s_nop 1
	v_add_f32_dpp v240, v240, v240 row_bcast:31 row_mask:0xc bank_mask:0xf
	v_mad_u32_u16 v76, v66, s58, v200 op_sel:[1,0,0,0]
	s_cmpk_gt_i32 s98, 0x5fff
	s_cbranch_scc1 .Lp7c_sk2_b
	s_ashr_i32 s99, s98, 31
	s_lshl_b64 s[100:101], s[98:99], 6
	v_lshl_add_u64 v[242:243], v[184:185], 0, s[100:101]
	s_and_saveexec_b64 s[18:19], s[82:83]
	global_store_dword v[242:243], v240, off
	s_mov_b64 exec, s[18:19]
; #define P7C_LOADA(R0, R1, C, S, X, t) do { const int tt_ = (t) < NT_TOK ? (t) : NT_TOK - 1; const unsigned char* rp_ = rp0 + (size_t)tt_ * 256; R0 = *(const v4u*)rp_; R1 = *(const v4u*)(rp_ + 16); \
;             C = *(const v4u*)(cp0 + (size_t)tt_ * 128); S = SCQ[tt_]; X = *(const unsigned*)(X2Bw + (size_t)tt_ * DM + 128 * hs + 16 * seg + 2 * r); } while (0)
; #define P7C_ISSUE(G, R0, R1) do { __builtin_amdgcn_s_setprio(3); _Pragma("unroll") for (int i_ = 0; i_ < 16; ++i_) { const unsigned e_ = P7_EID(R0, R1, i_); G[i_] = *(const v4u*)(Vb + (size_t)e_ * 128); } __builtin_amdgcn_s_setprio(0); } while (0)
; __device__ __forceinline__ void p7c_vaxpy(Frame& F, unsigned* bar, unsigned x, unsigned rank) {
;     ...
;         v4u GA[16], GB[16], ra0, ra1, ca, rb0, rb1, cb, cA, cB; float sa, sb, sA, sB; unsigned xa, xb2, xA, xB;
;         P7C_LOADA(ra0, ra1, ca, sa, xa, gwl);
;         P7C_LOADA(rb0, rb1, cb, sb, xb2, gwl + stride);
;         P7C_ISSUE(GA, ra0, ra1); cA = ca; sA = sa; xA = xa;
; #pragma unroll 1
;         for (int t = gwl; t < NT_TOK; t += 2 * stride) {
;             P7C_LOADA(ra0, ra1, ca, sa, xa, t + 2 * stride); P7C_ISSUE(GB, rb0, rb1); cB = cb; sB = sb; xB = xb2; P7C_COMP(GA, cA, sA, xA, t);
.Lp7c_sk2_b:
	global_load_dwordx4 v[80:83], v64, s[56:57]
	global_load_dwordx4 v[84:87], v76, s[56:57]
	v_mad_u32_u16 v64, v67, s58, v200 op_sel:[0,0,0,0]
	v_mad_u32_u16 v66, v67, s58, v200 op_sel:[1,0,0,0]
	global_load_dwordx4 v[88:91], v64, s[56:57]
	global_load_dwordx4 v[92:95], v66, s[56:57]
	s_setprio 0
	s_waitcnt vmcnt(33)
	ds_write_b128 v208, v[48:51]
	ds_write_b128 v209, v[52:55] offset:1024
	ds_write_b128 v210, v[68:71] offset:2048
	ds_write_b128 v211, v[72:75] offset:3072
	ds_read_b64_tr_b8 v[240:241], v212
	ds_read_b64_tr_b8 v[242:243], v213
	ds_read_b64_tr_b8 v[244:245], v214
	ds_read_b64_tr_b8 v[246:247], v215
	ds_read_b64_tr_b8 v[248:249], v216
	ds_read_b64_tr_b8 v[250:251], v217
	ds_read_b64_tr_b8 v[252:253], v218
	ds_read_b64_tr_b8 v[228:229], v219
	s_waitcnt lgkmcnt(4)
	s_waitcnt vmcnt(29)
	ds_write_b128 v208, v[32:35] offset:4096
	ds_write_b128 v209, v[36:39] offset:5120
	ds_write_b128 v210, v[56:59] offset:6144
	ds_write_b128 v211, v[60:63] offset:7168
	ds_read_b64_tr_b8 v[48:49], v212 offset:4096
	ds_read_b64_tr_b8 v[50:51], v213 offset:4096
	ds_read_b64_tr_b8 v[52:53], v214 offset:4096
	ds_read_b64_tr_b8 v[54:55], v215 offset:4096
	v_dot4_i32_i8 v232, v240, v220, 0
	v_dot4_i32_i8 v233, v242, v220, 0
	v_dot4_i32_i8 v234, v244, v220, 0
	v_dot4_i32_i8 v235, v246, v220, 0
	v_dot4_i32_i8 v232, v241, v224, v232
	v_dot4_i32_i8 v233, v243, v224, v233
	v_dot4_i32_i8 v234, v245, v224, v234
	v_dot4_i32_i8 v235, v247, v224, v235
	s_waitcnt lgkmcnt(8)
	ds_read_b64_tr_b8 v[240:241], v216 offset:4096
	ds_read_b64_tr_b8 v[242:243], v217 offset:4096
	ds_read_b64_tr_b8 v[244:245], v218 offset:4096
	ds_read_b64_tr_b8 v[246:247], v219 offset:4096
	v_dot4_i32_i8 v236, v248, v220, 0
	v_dot4_i32_i8 v237, v250, v220, 0
	v_dot4_i32_i8 v238, v252, v220, 0
	v_dot4_i32_i8 v239, v228, v220, 0
	v_dot4_i32_i8 v236, v249, v224, v236
	v_dot4_i32_i8 v237, v251, v224, v237
	v_dot4_i32_i8 v238, v253, v224, v238
	v_dot4_i32_i8 v239, v229, v224, v239
	s_waitcnt lgkmcnt(4)
	s_waitcnt vmcnt(25)
	ds_write_b128 v208, v[16:19] offset:8192
	ds_write_b128 v209, v[20:23] offset:9216
	ds_write_b128 v210, v[40:43] offset:10240
	ds_write_b128 v211, v[44:47] offset:11264
	ds_read_b64_tr_b8 v[248:249], v212 offset:8192
	ds_read_b64_tr_b8 v[250:251], v213 offset:8192
	ds_read_b64_tr_b8 v[252:253], v214 offset:8192
	ds_read_b64_tr_b8 v[228:229], v215 offset:8192
	v_dot4_i32_i8 v232, v48, v221, v232
	v_dot4_i32_i8 v233, v50, v221, v233
	v_dot4_i32_i8 v234, v52, v221, v234
	v_dot4_i32_i8 v235, v54, v221, v235
	v_dot4_i32_i8 v232, v49, v225, v232
	v_dot4_i32_i8 v233, v51, v225, v233
	v_dot4_i32_i8 v234, v53, v225, v234
	v_dot4_i32_i8 v235, v55, v225, v235
	s_waitcnt lgkmcnt(8)
	ds_read_b64_tr_b8 v[48:49], v216 offset:8192
	ds_read_b64_tr_b8 v[50:51], v217 offset:8192
	ds_read_b64_tr_b8 v[52:53], v218 offset:8192
	ds_read_b64_tr_b8 v[54:55], v219 offset:8192
	v_dot4_i32_i8 v236, v240, v221, v236
	v_dot4_i32_i8 v237, v242, v221, v237
	v_dot4_i32_i8 v238, v244, v221, v238
	v_dot4_i32_i8 v239, v246, v221, v239
	v_dot4_i32_i8 v236, v241, v225, v236
	v_dot4_i32_i8 v237, v243, v225, v237
	v_dot4_i32_i8 v238, v245, v225, v238
	v_dot4_i32_i8 v239, v247, v225, v239
	s_waitcnt lgkmcnt(4)
	s_waitcnt vmcnt(21)
	ds_write_b128 v208, v[8:11] offset:12288
	ds_write_b128 v209, v[12:15] offset:13312
	ds_write_b128 v210, v[24:27] offset:14336
	ds_write_b128 v211, v[28:31] offset:15360
	ds_read_b64_tr_b8 v[240:241], v212 offset:12288
	ds_read_b64_tr_b8 v[242:243], v213 offset:12288
	ds_read_b64_tr_b8 v[244:245], v214 offset:12288
	ds_read_b64_tr_b8 v[246:247], v215 offset:12288
	v_dot4_i32_i8 v232, v248, v222, v232
	v_dot4_i32_i8 v233, v250, v222, v233
	v_dot4_i32_i8 v234, v252, v222, v234
	v_dot4_i32_i8 v235, v228, v222, v235
	v_dot4_i32_i8 v232, v249, v226, v232
	v_dot4_i32_i8 v233, v251, v226, v233
	v_dot4_i32_i8 v234, v253, v226, v234
	v_dot4_i32_i8 v235, v229, v226, v235
	s_waitcnt lgkmcnt(8)
	ds_read_b64_tr_b8 v[248:249], v216 offset:12288
	ds_read_b64_tr_b8 v[250:251], v217 offset:12288
	ds_read_b64_tr_b8 v[252:253], v218 offset:12288
	ds_read_b64_tr_b8 v[228:229], v219 offset:12288
	v_dot4_i32_i8 v236, v48, v222, v236
	v_dot4_i32_i8 v237, v50, v222, v237
	v_dot4_i32_i8 v238, v52, v222, v238
	v_dot4_i32_i8 v239, v54, v222, v239
	v_dot4_i32_i8 v236, v49, v226, v236
	v_dot4_i32_i8 v237, v51, v226, v237
	v_dot4_i32_i8 v238, v53, v226, v238
	v_dot4_i32_i8 v239, v55, v226, v239
	s_waitcnt lgkmcnt(4)
	v_dot4_i32_i8 v232, v240, v223, v232
	v_dot4_i32_i8 v233, v242, v223, v233
	v_dot4_i32_i8 v234, v244, v223, v234
	v_dot4_i32_i8 v235, v246, v223, v235
	v_dot4_i32_i8 v232, v241, v227, v232
	v_dot4_i32_i8 v233, v243, v227, v233
	v_dot4_i32_i8 v234, v245, v227, v234
	v_dot4_i32_i8 v235, v247, v227, v235
	s_waitcnt lgkmcnt(0)
	v_dot4_i32_i8 v236, v248, v223, v236
	v_dot4_i32_i8 v237, v250, v223, v237
	v_dot4_i32_i8 v238, v252, v223, v238
	v_dot4_i32_i8 v239, v228, v223, v239
	v_dot4_i32_i8 v236, v249, v227, v236
	v_dot4_i32_i8 v237, v251, v227, v237
	v_dot4_i32_i8 v238, v253, v227, v238
	v_dot4_i32_i8 v239, v229, v227, v239
	v_mov_b32_e32 v204, v206
	v_mov_b32_e32 v205, v207
	s_add_i32 s18, s24, s20
	s_min_i32 s18, s18, 0x5fff
	s_ashr_i32 s19, s18, 31
	s_lshl_b64 s[28:29], s[18:19], 8
	s_waitcnt lgkmcnt(0)
	v_lshl_add_u64 v[8:9], v[158:159], 0, s[28:29]
	s_lshl_b64 s[28:29], s[18:19], 7
	global_load_dwordx4 v[64:67], v[8:9], off offset:16
	global_load_dwordx4 v[76:79], v[8:9], off
	v_lshl_add_u64 v[8:9], v[160:161], 0, s[28:29]
	s_lshl_b64 s[28:29], s[18:19], 2
	s_add_u32 s28, s54, s28
	s_addc_u32 s29, s55, s29
	s_lshl_b64 s[18:19], s[18:19], 12
	v_lshl_add_u64 v[10:11], v[182:183], 0, s[18:19]
	global_load_dwordx4 v[152:155], v[8:9], off
	global_load_dword v207, v157, s[28:29]
	global_load_dword v206, v[10:11], off
	s_setprio 3
	s_waitcnt vmcnt(24)
; #define P7C_LOADA(R0, R1, C, S, X, t) do { const int tt_ = (t) < NT_TOK ? (t) : NT_TOK - 1; const unsigned char* rp_ = rp0 + (size_t)tt_ * 256; R0 = *(const v4u*)rp_; R1 = *(const v4u*)(rp_ + 16); \
;             C = *(const v4u*)(cp0 + (size_t)tt_ * 128); S = SCQ[tt_]; X = *(const unsigned*)(X2Bw + (size_t)tt_ * DM + 128 * hs + 16 * seg + 2 * r); } while (0)
; #define P7C_ISSUE(G, R0, R1) do { __builtin_amdgcn_s_setprio(3); _Pragma("unroll") for (int i_ = 0; i_ < 16; ++i_) { const unsigned e_ = P7_EID(R0, R1, i_); G[i_] = *(const v4u*)(Vb + (size_t)e_ * 128); } __builtin_amdgcn_s_setprio(0); } while (0)
; __device__ __forceinline__ void p7c_vaxpy(Frame& F, unsigned* bar, unsigned x, unsigned rank) {
;     ...
;         v4u GA[16], GB[16], ra0, ra1, ca, rb0, rb1, cb, cA, cB; float sa, sb, sA, sB; unsigned xa, xb2, xA, xB;
;         P7C_LOADA(ra0, ra1, ca, sa, xa, gwl);
;         P7C_LOADA(rb0, rb1, cb, sb, xb2, gwl + stride);
;         P7C_ISSUE(GA, ra0, ra1); cA = ca; sA = sa; xA = xa;
; #pragma unroll 1
;         for (int t = gwl; t < NT_TOK; t += 2 * stride) {
;             P7C_LOADA(ra0, ra1, ca, sa, xa, t + 2 * stride); P7C_ISSUE(GB, rb0, rb1); cB = cb; sB = sb; xB = xb2; P7C_COMP(GA, cA, sA, xA, t);
;             P7C_LOADA(rb0, rb1, cb, sb, xb2, t + 3 * stride); P7C_ISSUE(GA, ra0, ra1); cA = ca; sA = sa; xA = xa; P7C_COMP(GB, cB, sB, xB, t + stride);
	v_permlane32_swap_b32_e32 v232, v236
	v_permlane32_swap_b32_e32 v233, v237
	v_mad_u32_u16 v8, v148, s58, v200 op_sel:[0,0,0,0]
	v_permlane32_swap_b32_e32 v234, v238
	v_permlane32_swap_b32_e32 v235, v239
	v_mad_u32_u16 v10, v148, s58, v200 op_sel:[1,0,0,0]
	v_add_u32_e32 v232, v232, v236
	global_load_dwordx4 v[48:51], v8, s[56:57]
	v_add_u32_e32 v233, v233, v237
	global_load_dwordx4 v[52:55], v10, s[56:57]
	v_add_u32_e32 v234, v234, v238
	v_add_u32_e32 v235, v235, v239
	v_mad_u32_u16 v8, v149, s58, v200 op_sel:[0,0,0,0]
	s_nop 1
	v_permlane16_swap_b32_e32 v232, v234
	v_mad_u32_u16 v10, v149, s58, v200 op_sel:[1,0,0,0]
	v_permlane16_swap_b32_e32 v233, v235
	global_load_dwordx4 v[68:71], v8, s[56:57]
	v_add_u32_e32 v232, v232, v234
	global_load_dwordx4 v[72:75], v10, s[56:57]
	v_add_u32_e32 v233, v233, v235
	s_nop 1
	v_mad_u32_u16 v8, v150, s58, v200 op_sel:[0,0,0,0]
	v_mov_b32_dpp v234, v232 quad_perm:[1,0,3,2] row_mask:0xf bank_mask:0xf
	v_mov_b32_dpp v235, v233 quad_perm:[1,0,3,2] row_mask:0xf bank_mask:0xf
	v_mad_u32_u16 v10, v150, s58, v200 op_sel:[1,0,0,0]
	v_cndmask_b32_e64 v236, v235, v232, s[44:45]
	global_load_dwordx4 v[32:35], v8, s[56:57]
	v_cndmask_b32_e64 v237, v233, v234, s[44:45]
	global_load_dwordx4 v[36:39], v10, s[56:57]
	v_cvt_f32_i32_e32 v236, v236
	v_cvt_f32_i32_e32 v237, v237
	v_mad_u32_u16 v8, v151, s58, v200 op_sel:[0,0,0,0]
	v_lshlrev_b32_e32 v238, 16, v204
	v_and_b32_e32 v239, 0xffff0000, v204
	v_mad_u32_u16 v10, v151, s58, v200 op_sel:[1,0,0,0]
	v_fmac_f32_e32 v238, v205, v236
	global_load_dwordx4 v[56:59], v8, s[56:57]
	v_fmac_f32_e32 v239, v205, v237
	global_load_dwordx4 v[60:63], v10, s[56:57]
	v_mul_f32_e32 v240, v239, v239
	v_fmac_f32_e32 v240, v238, v238
	v_mad_u32_u16 v8, v144, s58, v200 op_sel:[0,0,0,0]
	v_cvt_pk_bf16_f32 v244, v238, v239
	global_store_dword v[188:189], v244, off
	v_mad_u32_u16 v10, v144, s58, v200 op_sel:[1,0,0,0]
	s_nop 1
	global_load_dwordx4 v[16:19], v8, s[56:57]
	v_add_f32_dpp v240, v240, v240 quad_perm:[1,0,3,2] row_mask:0xf bank_mask:0xf
	global_load_dwordx4 v[20:23], v10, s[56:57]
	s_nop 1
	v_add_f32_dpp v240, v240, v240 quad_perm:[2,3,0,1] row_mask:0xf bank_mask:0xf
	v_mad_u32_u16 v8, v145, s58, v200 op_sel:[0,0,0,0]
	s_nop 1
	v_add_f32_dpp v240, v240, v240 row_half_mirror row_mask:0xf bank_mask:0xf
	v_mad_u32_u16 v10, v145, s58, v200 op_sel:[1,0,0,0]
	s_nop 1
	global_load_dwordx4 v[40:43], v8, s[56:57]
	v_add_f32_dpp v240, v240, v240 row_mirror row_mask:0xf bank_mask:0xf
	global_load_dwordx4 v[44:47], v10, s[56:57]
	s_nop 1
	v_add_f32_dpp v240, v240, v240 row_bcast:15 row_mask:0xa bank_mask:0xf
	v_mad_u32_u16 v8, v146, s58, v200 op_sel:[0,0,0,0]
	s_nop 1
	v_add_f32_dpp v240, v240, v240 row_bcast:31 row_mask:0xc bank_mask:0xf
	v_mad_u32_u16 v12, v146, s58, v200 op_sel:[1,0,0,0]
	s_and_saveexec_b64 s[18:19], s[82:83]
	global_store_dword v[186:187], v240, off
	s_mov_b64 exec, s[18:19]
	v_mad_u32_u16 v24, v147, s58, v200 op_sel:[0,0,0,0]
	v_mad_u32_u16 v28, v147, s58, v200 op_sel:[1,0,0,0]
	global_load_dwordx4 v[8:11], v8, s[56:57]
	s_nop 0
	global_load_dwordx4 v[12:15], v12, s[56:57]
	s_nop 0
	global_load_dwordx4 v[24:27], v24, s[56:57]
	s_nop 0
	global_load_dwordx4 v[28:31], v28, s[56:57]
	s_setprio 0
	s_mov_b64 vcc, s[40:41]
	v_cndmask_b32_dpp v220, v4, v4, vcc row_ror:8 row_mask:0xf bank_mask:0xf
	v_cndmask_b32_dpp v221, v5, v5, vcc row_ror:8 row_mask:0xf bank_mask:0xf
	v_cndmask_b32_dpp v222, v6, v6, vcc row_ror:8 row_mask:0xf bank_mask:0xf
	v_cndmask_b32_dpp v223, v7, v7, vcc row_ror:8 row_mask:0xf bank_mask:0xf
	s_mov_b64 vcc, s[60:61]
	v_cndmask_b32_dpp v224, v4, v4, vcc row_ror:8 row_mask:0xf bank_mask:0xf
	v_cndmask_b32_dpp v225, v5, v5, vcc row_ror:8 row_mask:0xf bank_mask:0xf
	v_cndmask_b32_dpp v226, v6, v6, vcc row_ror:8 row_mask:0xf bank_mask:0xf
	v_cndmask_b32_dpp v227, v7, v7, vcc row_ror:8 row_mask:0xf bank_mask:0xf
	s_waitcnt vmcnt(34)
	ds_write_b128 v208, v[128:131]
	ds_write_b128 v209, v[132:135] offset:1024
	ds_write_b128 v210, v[136:139] offset:2048
	ds_write_b128 v211, v[140:143] offset:3072
	ds_read_b64_tr_b8 v[240:241], v212
	ds_read_b64_tr_b8 v[242:243], v213
	ds_read_b64_tr_b8 v[244:245], v214
	ds_read_b64_tr_b8 v[246:247], v215
	ds_read_b64_tr_b8 v[248:249], v216
	ds_read_b64_tr_b8 v[250:251], v217
	ds_read_b64_tr_b8 v[252:253], v218
	ds_read_b64_tr_b8 v[228:229], v219
	s_waitcnt lgkmcnt(4)
	s_waitcnt vmcnt(30)
; #define P7C_LOADA(R0, R1, C, S, X, t) do { const int tt_ = (t) < NT_TOK ? (t) : NT_TOK - 1; const unsigned char* rp_ = rp0 + (size_t)tt_ * 256; R0 = *(const v4u*)rp_; R1 = *(const v4u*)(rp_ + 16); \
;             C = *(const v4u*)(cp0 + (size_t)tt_ * 128); S = SCQ[tt_]; X = *(const unsigned*)(X2Bw + (size_t)tt_ * DM + 128 * hs + 16 * seg + 2 * r); } while (0)
; #define P7C_ISSUE(G, R0, R1) do { __builtin_amdgcn_s_setprio(3); _Pragma("unroll") for (int i_ = 0; i_ < 16; ++i_) { const unsigned e_ = P7_EID(R0, R1, i_); G[i_] = *(const v4u*)(Vb + (size_t)e_ * 128); } __builtin_amdgcn_s_setprio(0); } while (0)
; __device__ __forceinline__ void p7c_vaxpy(Frame& F, unsigned* bar, unsigned x, unsigned rank) {
;     ...
;         v4u GA[16], GB[16], ra0, ra1, ca, rb0, rb1, cb, cA, cB; float sa, sb, sA, sB; unsigned xa, xb2, xA, xB;
;         P7C_LOADA(ra0, ra1, ca, sa, xa, gwl);
;         P7C_LOADA(rb0, rb1, cb, sb, xb2, gwl + stride);
;         P7C_ISSUE(GA, ra0, ra1); cA = ca; sA = sa; xA = xa;
; #pragma unroll 1
;         for (int t = gwl; t < NT_TOK; t += 2 * stride) {
;             P7C_LOADA(ra0, ra1, ca, sa, xa, t + 2 * stride); P7C_ISSUE(GB, rb0, rb1); cB = cb; sB = sb; xB = xb2; P7C_COMP(GA, cA, sA, xA, t);
;             P7C_LOADA(rb0, rb1, cb, sb, xb2, t + 3 * stride); P7C_ISSUE(GA, ra0, ra1); cA = ca; sA = sa; xA = xa; P7C_COMP(GB, cB, sB, xB, t + stride);
	ds_write_b128 v208, v[112:115] offset:4096
	ds_write_b128 v209, v[116:119] offset:5120
	ds_write_b128 v210, v[120:123] offset:6144
	ds_write_b128 v211, v[124:127] offset:7168
	ds_read_b64_tr_b8 v[128:129], v212 offset:4096
	ds_read_b64_tr_b8 v[130:131], v213 offset:4096
	ds_read_b64_tr_b8 v[132:133], v214 offset:4096
	ds_read_b64_tr_b8 v[134:135], v215 offset:4096
	v_dot4_i32_i8 v232, v240, v220, 0
	v_dot4_i32_i8 v233, v242, v220, 0
	v_dot4_i32_i8 v234, v244, v220, 0
	v_dot4_i32_i8 v235, v246, v220, 0
	v_dot4_i32_i8 v232, v241, v224, v232
	v_dot4_i32_i8 v233, v243, v224, v233
	v_dot4_i32_i8 v234, v245, v224, v234
	v_dot4_i32_i8 v235, v247, v224, v235
	s_waitcnt lgkmcnt(8)
	ds_read_b64_tr_b8 v[240:241], v216 offset:4096
	ds_read_b64_tr_b8 v[242:243], v217 offset:4096
	ds_read_b64_tr_b8 v[244:245], v218 offset:4096
	ds_read_b64_tr_b8 v[246:247], v219 offset:4096
	v_dot4_i32_i8 v236, v248, v220, 0
	v_dot4_i32_i8 v237, v250, v220, 0
	v_dot4_i32_i8 v238, v252, v220, 0
	v_dot4_i32_i8 v239, v228, v220, 0
	v_dot4_i32_i8 v236, v249, v224, v236
	v_dot4_i32_i8 v237, v251, v224, v237
	v_dot4_i32_i8 v238, v253, v224, v238
	v_dot4_i32_i8 v239, v229, v224, v239
	s_waitcnt lgkmcnt(4)
	s_waitcnt vmcnt(26)
	ds_write_b128 v208, v[96:99] offset:8192
	ds_write_b128 v209, v[100:103] offset:9216
	ds_write_b128 v210, v[104:107] offset:10240
	ds_write_b128 v211, v[108:111] offset:11264
	ds_read_b64_tr_b8 v[248:249], v212 offset:8192
	ds_read_b64_tr_b8 v[250:251], v213 offset:8192
	ds_read_b64_tr_b8 v[252:253], v214 offset:8192
	ds_read_b64_tr_b8 v[228:229], v215 offset:8192
	v_dot4_i32_i8 v232, v128, v221, v232
	v_dot4_i32_i8 v233, v130, v221, v233
	v_dot4_i32_i8 v234, v132, v221, v234
	v_dot4_i32_i8 v235, v134, v221, v235
	v_dot4_i32_i8 v232, v129, v225, v232
	v_dot4_i32_i8 v233, v131, v225, v233
	v_dot4_i32_i8 v234, v133, v225, v234
	v_dot4_i32_i8 v235, v135, v225, v235
	s_waitcnt lgkmcnt(8)
	ds_read_b64_tr_b8 v[128:129], v216 offset:8192
	ds_read_b64_tr_b8 v[130:131], v217 offset:8192
	ds_read_b64_tr_b8 v[132:133], v218 offset:8192
	ds_read_b64_tr_b8 v[134:135], v219 offset:8192
	v_dot4_i32_i8 v236, v240, v221, v236
	v_dot4_i32_i8 v237, v242, v221, v237
	v_dot4_i32_i8 v238, v244, v221, v238
	v_dot4_i32_i8 v239, v246, v221, v239
	v_dot4_i32_i8 v236, v241, v225, v236
	v_dot4_i32_i8 v237, v243, v225, v237
	v_dot4_i32_i8 v238, v245, v225, v238
	v_dot4_i32_i8 v239, v247, v225, v239
	s_waitcnt lgkmcnt(4)
	s_waitcnt vmcnt(22)
	ds_write_b128 v208, v[80:83] offset:12288
	ds_write_b128 v209, v[84:87] offset:13312
	ds_write_b128 v210, v[88:91] offset:14336
	ds_write_b128 v211, v[92:95] offset:15360
	ds_read_b64_tr_b8 v[240:241], v212 offset:12288
	ds_read_b64_tr_b8 v[242:243], v213 offset:12288
	ds_read_b64_tr_b8 v[244:245], v214 offset:12288
	ds_read_b64_tr_b8 v[246:247], v215 offset:12288
	v_dot4_i32_i8 v232, v248, v222, v232
	v_dot4_i32_i8 v233, v250, v222, v233
	v_dot4_i32_i8 v234, v252, v222, v234
	v_dot4_i32_i8 v235, v228, v222, v235
	v_dot4_i32_i8 v232, v249, v226, v232
	v_dot4_i32_i8 v233, v251, v226, v233
	v_dot4_i32_i8 v234, v253, v226, v234
	v_dot4_i32_i8 v235, v229, v226, v235
	s_waitcnt lgkmcnt(8)
	ds_read_b64_tr_b8 v[248:249], v216 offset:12288
	ds_read_b64_tr_b8 v[250:251], v217 offset:12288
	ds_read_b64_tr_b8 v[252:253], v218 offset:12288
	ds_read_b64_tr_b8 v[228:229], v219 offset:12288
	v_dot4_i32_i8 v236, v128, v222, v236
	v_dot4_i32_i8 v237, v130, v222, v237
	v_dot4_i32_i8 v238, v132, v222, v238
	v_dot4_i32_i8 v239, v134, v222, v239
	v_dot4_i32_i8 v236, v129, v226, v236
	v_dot4_i32_i8 v237, v131, v226, v237
	v_dot4_i32_i8 v238, v133, v226, v238
	v_dot4_i32_i8 v239, v135, v226, v239
	s_waitcnt lgkmcnt(4)
	v_dot4_i32_i8 v232, v240, v223, v232
	v_dot4_i32_i8 v233, v242, v223, v233
	v_dot4_i32_i8 v234, v244, v223, v234
	v_dot4_i32_i8 v235, v246, v223, v235
	v_dot4_i32_i8 v232, v241, v227, v232
	v_dot4_i32_i8 v233, v243, v227, v233
	v_dot4_i32_i8 v234, v245, v227, v234
	v_dot4_i32_i8 v235, v247, v227, v235
	s_waitcnt lgkmcnt(0)
	v_dot4_i32_i8 v236, v248, v223, v236
	v_dot4_i32_i8 v237, v250, v223, v237
	v_dot4_i32_i8 v238, v252, v223, v238
	v_dot4_i32_i8 v239, v228, v223, v239
	v_dot4_i32_i8 v236, v249, v227, v236
	v_dot4_i32_i8 v237, v251, v227, v237
	v_dot4_i32_i8 v238, v253, v227, v238
	v_dot4_i32_i8 v239, v229, v227, v239
	v_mov_b32_e32 v204, v199
	v_mov_b32_e32 v205, v198
	s_add_i32 s98, s23, s20
	s_branch .LBB0_1088

.Lp7c_sk1_d:
	s_nop 1
	v_add_f32_dpp v240, v240, v240 quad_perm:[1,0,3,2] row_mask:0xf bank_mask:0xf
	s_nop 1
	v_add_f32_dpp v240, v240, v240 quad_perm:[2,3,0,1] row_mask:0xf bank_mask:0xf
	s_nop 1
	v_add_f32_dpp v240, v240, v240 row_half_mirror row_mask:0xf bank_mask:0xf
	s_nop 1
	v_add_f32_dpp v240, v240, v240 row_mirror row_mask:0xf bank_mask:0xf
	s_nop 1
	v_add_f32_dpp v240, v240, v240 row_bcast:15 row_mask:0xa bank_mask:0xf
	s_nop 1
	v_add_f32_dpp v240, v240, v240 row_bcast:31 row_mask:0xc bank_mask:0xf
	s_cmpk_gt_i32 s98, 0x5fff
	s_cbranch_scc1 .Lp7c_sk2_d
	s_ashr_i32 s99, s98, 31
	s_lshl_b64 s[100:101], s[98:99], 6
	v_lshl_add_u64 v[242:243], v[184:185], 0, s[100:101]
	s_and_saveexec_b64 s[18:19], s[82:83]
	global_store_dword v[242:243], v240, off
	s_mov_b64 exec, s[18:19]
